# diff loop: same moved work, spread more evenly over the PV MFMA slots (5 per slot)
# speedup vs baseline: 1.0025x; 1.0025x over previous
; template <int D0> __device__ __forceinline__ void pv_one(f32x16& od, int vb, bf16x8 pa0, bf16x8 pa1, bf16x8 pa2, bf16x8 pa3) {
;     const s16x4 l0 = tr_read<v_rd_off(D0, 0, 0)>(vb), h0 = tr_read<v_rd_off(D0, 0, 1)>(vb), l1 = tr_read<v_rd_off(D0, 1, 0)>(vb), h1 = tr_read<v_rd_off(D0, 1, 1)>(vb);
;     const s16x4 l2 = tr_read<v_rd_off(D0, 2, 0)>(vb), h2 = tr_read<v_rd_off(D0, 2, 1)>(vb), l3 = tr_read<v_rd_off(D0, 3, 0)>(vb), h3 = tr_read<v_rd_off(D0, 3, 1)>(vb);
;     asm volatile("s_waitcnt lgkmcnt(0)" ::: "memory"); SBAR();
;     ...
;     od = __builtin_amdgcn_mfma_f32_32x32x16_bf16(pa0, PK(l0, h0), od, 0, 0, 0);
;     od = __builtin_amdgcn_mfma_f32_32x32x16_bf16(pa1, PK(l1, h1), od, 0, 0, 0);
;     od = __builtin_amdgcn_mfma_f32_32x32x16_bf16(pa2, PK(l2, h2), od, 0, 0, 0);
;     od = __builtin_amdgcn_mfma_f32_32x32x16_bf16(pa3, PK(l3, h3), od, 0, 0, 0);
;     ...
; }
; __device__ __forceinline__ void pv_d0(f32x16* o, int vb, bf16x8 pa0, bf16x8 pa1, bf16x8 pa2, bf16x8 pa3) {
;     pv_one<0>(o[0], vb, pa0, pa1, pa2, pa3); pv_one<1>(o[1], vb, pa0, pa1, pa2, pa3); pv_one<2>(o[2], vb, pa0, pa1, pa2, pa3); pv_one<3>(o[3], vb, pa0, pa1, pa2, pa3);
; }
; __device__ __forceinline__ void partialSM(f32x16& p0, f32x16& p1, float& m_reg, float& mn, float& alpha, const float C, const float thr) {
;     float pmax = p0[0];
; #pragma unroll
;     for (int r = 1; r < 16; ++r) pmax = fmaxf(pmax, p0[r]);
; #pragma unroll
;     for (int r = 0; r < 16; ++r) pmax = fmaxf(pmax, p1[r]);
;     { auto rr = __builtin_amdgcn_permlane32_swap(__float_as_uint(pmax), __float_as_uint(pmax), false, false);
;       pmax = fmaxf(__uint_as_float(rr[0]), __uint_as_float(rr[1])); }
;     if (__builtin_expect(__all(pmax - m_reg <= thr), 1)) { mn = m_reg; alpha = 1.f; }
;     else { mn = fmaxf(m_reg, pmax); alpha = __builtin_amdgcn_exp2f((m_reg - mn) * C); m_reg = mn; }
;     const float mnC = -mn * C;
; #pragma unroll
;     for (int r = 0; r < 16; ++r) p0[r] = fmaf(p0[r], C, mnC);
; #pragma unroll
;     for (int r = 0; r < 16; ++r) p1[r] = fmaf(p1[r], C, mnC);
; #pragma unroll
;     for (int r = 0; r < 16; ++r) p0[r] = __builtin_amdgcn_exp2f(p0[r]);
; }
; __device__ __forceinline__ void finishSM(f32x16& p0, f32x16& p1, float alpha, float& l_reg, bf16x8& pa0, bf16x8& pa1, bf16x8& pa2, bf16x8& pa3) {
; #pragma unroll
;     for (int r = 0; r < 16; ++r) p1[r] = __builtin_amdgcn_exp2f(p1[r]);
;     float ps = 0;
.LBB0_171:
	s_add_i32 s37, s52, -3
	ds_read_b128 v[64:67], v186 offset:40960
	ds_read_b128 v[68:71], v186 offset:45056
	v_exp_f32_e32 v143, v138
	v_add_f32_e32 v138, 0, v217
	v_add_f32_e32 v138, v219, v138
	s_waitcnt lgkmcnt(1)
	v_mfma_f32_32x32x16_bf16 v[80:95], v[64:67], v[110:113], 0
	v_add_f32_e32 v138, v208, v138
	v_add_f32_e32 v138, v218, v138
	v_add_f32_e32 v138, v153, v138
	ds_read_b128 v[204:207], v188 offset:40960
	ds_read_b128 v[220:223], v188 offset:45056
	v_add_f32_e32 v138, v216, v138
	v_add_f32_e32 v138, v152, v138
	v_add_f32_e32 v138, v202, v138
	s_waitcnt lgkmcnt(2)
	v_mfma_f32_32x32x16_bf16 v[64:79], v[68:71], v[110:113], 0
	v_add_f32_e32 v138, v149, v138
	v_add_f32_e32 v138, v151, v138
	v_add_f32_e32 v138, v147, v138
	v_add_f32_e32 v138, v150, v138
	v_add_f32_e32 v138, v145, v138
	v_exp_f32_e32 v191, v139
	v_add_f32_e32 v138, v148, v138
	s_waitcnt lgkmcnt(1)
	v_mfma_f32_32x32x16_bf16 v[80:95], v[204:207], v[106:109], v[80:95]
	v_exp_f32_e32 v136, v136
	v_add_f32_e32 v138, v144, v138
	v_exp_f32_e32 v137, v137
	v_add_f32_e32 v138, v146, v138
	v_exp_f32_e32 v130, v130
	v_add_f32_e32 v138, v143, v138
	v_exp_f32_e32 v131, v131
	s_waitcnt lgkmcnt(0)
	v_mfma_f32_32x32x16_bf16 v[64:79], v[220:223], v[106:109], v[64:79]
	ds_read_b128 v[204:207], v190 offset:40960
	ds_read_b128 v[220:223], v190 offset:45056
	v_add_f32_e32 v138, v191, v138
	v_exp_f32_e32 v128, v128
	v_add_f32_e32 v138, v136, v138
	v_exp_f32_e32 v129, v129
	v_add_f32_e32 v138, v137, v138
	v_exp_f32_e32 v126, v126
	s_waitcnt lgkmcnt(1)
	v_mfma_f32_32x32x16_bf16 v[80:95], v[204:207], v[102:105], v[80:95]
	v_add_f32_e32 v138, v130, v138
	v_exp_f32_e32 v127, v127
	v_add_f32_e32 v138, v131, v138
	v_exp_f32_e32 v200, v140
	v_add_f32_e32 v138, v128, v138
	v_exp_f32_e32 v210, v141
	v_add_f32_e32 v138, v129, v138
	s_waitcnt lgkmcnt(0)
	v_mfma_f32_32x32x16_bf16 v[64:79], v[220:223], v[102:105], v[64:79]
	ds_read_b128 v[204:207], v192 offset:40960
	ds_read_b128 v[220:223], v192 offset:45056
	v_exp_f32_e32 v134, v134
	v_add_f32_e32 v138, v126, v138
	v_exp_f32_e32 v135, v135
	v_add_f32_e32 v138, v127, v138
	v_exp_f32_e32 v132, v132
	v_add_f32_e32 v138, v200, v138
	s_waitcnt lgkmcnt(1)
	v_mfma_f32_32x32x16_bf16 v[80:95], v[204:207], v[98:101], v[80:95]
	v_exp_f32_e32 v133, v133
	v_add_f32_e32 v138, v210, v138
	v_add_f32_e32 v138, v134, v138
	v_add_f32_e32 v138, v135, v138
	v_add_f32_e32 v138, v132, v138
	v_add_f32_e32 v196, v133, v138
	v_mov_b32_e32 v198, v196
	s_waitcnt lgkmcnt(0)
	v_mfma_f32_32x32x16_bf16 v[64:79], v[220:223], v[98:101], v[64:79]
	ds_read_b64_tr_b16 v[220:221], v180 offset:0x1000
	ds_read_b64_tr_b16 v[222:223], v180 offset:0x1800
	ds_read_b64_tr_b16 v[224:225], v180 offset:0x2000
	ds_read_b64_tr_b16 v[226:227], v180 offset:0x2800
	ds_read_b64_tr_b16 v[228:229], v180 offset:0x3000
	ds_read_b64_tr_b16 v[230:231], v180 offset:0x3800
	v_cvt_pk_bf16_f32 v138, v217, v219
	v_cvt_pk_bf16_f32 v139, v208, v218
	v_cvt_pk_bf16_f32 v140, v153, v216
	ds_read_b64_tr_b16 v[216:217], v180 offset:0
	ds_read_b64_tr_b16 v[218:219], v180 offset:0x800
	v_permlane32_swap_b32_e32 v196, v198
	v_cvt_pk_bf16_f32 v141, v152, v202
	v_permlane32_swap_b32_e32 v138, v140
	v_cvt_pk_bf16_f32 v204, v149, v151
	v_cvt_pk_bf16_f32 v205, v147, v150
	v_cvt_pk_bf16_f32 v206, v145, v148
	v_cvt_pk_bf16_f32 v207, v144, v146
	v_cvt_pk_bf16_f32 v144, v143, v191
	v_cvt_pk_bf16_f32 v145, v136, v137
	v_cvt_pk_bf16_f32 v146, v130, v131
	v_cvt_pk_bf16_f32 v147, v128, v129
	v_cvt_pk_bf16_f32 v148, v126, v127
	v_cvt_pk_bf16_f32 v149, v200, v210
	v_cvt_pk_bf16_f32 v150, v134, v135
	v_cvt_pk_bf16_f32 v151, v132, v133
	v_permlane32_swap_b32_e32 v139, v141
	v_permlane32_swap_b32_e32 v204, v206
	v_permlane32_swap_b32_e32 v205, v207
	v_permlane32_swap_b32_e32 v144, v146
	v_permlane32_swap_b32_e32 v145, v147
	v_permlane32_swap_b32_e32 v148, v150
	v_permlane32_swap_b32_e32 v149, v151
	s_cmp_lt_u32 s37, 30
	s_cselect_b32 s14, 0, 0xffffffe0
	s_cselect_b32 s15, s18, s86
	s_add_i32 s14, s14, s52
	s_lshl_b32 s14, s14, 6
	s_add_i32 s14, s14, s15
	s_sub_i32 s14, s14, 64
	s_ashr_i32 s15, s14, 31
	v_lshl_add_u64 v[126:127], s[14:15], 0, v[164:165]
	v_lshl_add_u64 v[130:131], v[168:169], 0, s[14:15]
	v_mad_u64_u32 v[128:129], s[38:39], v126, s9, v[170:171]
	v_mad_u64_u32 v[132:133], s[38:39], v130, s9, v[170:171]
	v_mad_i32_i24 v129, v127, s9, v129
	v_mad_i32_i24 v133, v131, s9, v133
	v_mad_i64_i32 v[134:135], s[14:15], s14, v195, v[166:167]
	global_load_dwordx4 v[126:129], v[128:129], off
	s_nop 0
	global_load_dwordx4 v[130:133], v[132:133], off
	s_nop 0
	global_load_dwordx4 v[134:137], v[134:135], off
	s_waitcnt lgkmcnt(0)
	s_nop 0
	v_mfma_f32_32x32x16_bf16 v[48:63], v[138:141], v[216:219], v[48:63]
	ds_read_b64_tr_b16 v[216:217], v180 offset:0x200
	ds_read_b64_tr_b16 v[218:219], v180 offset:0xa00
	v_max_f32_e32 v238, v81, v81
	v_max_f32_e32 v239, v80, v80
	v_max_f32_e32 v238, v239, v238
	v_max3_f32 v238, v238, v82, v83
	v_max3_f32 v238, v238, v84, v85
	v_mfma_f32_32x32x16_bf16 v[48:63], v[204:207], v[220:223], v[48:63]
	ds_read_b64_tr_b16 v[220:221], v180 offset:0x1200
	ds_read_b64_tr_b16 v[222:223], v180 offset:0x1a00
	v_max3_f32 v238, v238, v86, v87
	v_max3_f32 v238, v238, v88, v89
	v_max3_f32 v238, v238, v90, v91
	v_max3_f32 v238, v238, v92, v93
	v_max3_f32 v238, v238, v94, v95
	v_mfma_f32_32x32x16_bf16 v[48:63], v[144:147], v[224:227], v[48:63]
	ds_read_b64_tr_b16 v[224:225], v180 offset:0x2200
	ds_read_b64_tr_b16 v[226:227], v180 offset:0x2a00
	v_max3_f32 v238, v238, v64, v65
	v_max3_f32 v238, v238, v66, v67
	v_max3_f32 v238, v238, v68, v69
	v_max3_f32 v238, v238, v70, v71
	v_max3_f32 v238, v238, v72, v73
	v_mfma_f32_32x32x16_bf16 v[48:63], v[148:151], v[228:231], v[48:63]
	ds_read_b64_tr_b16 v[228:229], v180 offset:0x3200
	ds_read_b64_tr_b16 v[230:231], v180 offset:0x3a00
	v_max3_f32 v238, v238, v74, v75
	v_max3_f32 v238, v238, v76, v77
	v_max3_f32 v238, v238, v78, v79
	v_mov_b32_e32 v239, v238
	s_nop 1
	s_waitcnt lgkmcnt(6)
; #define SBAR() __builtin_amdgcn_sched_barrier(0)
; template <int OFF> __device__ __forceinline__ s16x4 tr_read(int vb) { s16x4 r; asm volatile("ds_read_b64_tr_b16 %0, %1 offset:%2" : "=&v"(r) : "v"(vb), "i"(OFF) : "memory"); return r; }
; template <int D0> __device__ __forceinline__ void pv_one(f32x16& od, int vb, bf16x8 pa0, bf16x8 pa1, bf16x8 pa2, bf16x8 pa3) {
;     const s16x4 l0 = tr_read<v_rd_off(D0, 0, 0)>(vb), h0 = tr_read<v_rd_off(D0, 0, 1)>(vb), l1 = tr_read<v_rd_off(D0, 1, 0)>(vb), h1 = tr_read<v_rd_off(D0, 1, 1)>(vb);
;     const s16x4 l2 = tr_read<v_rd_off(D0, 2, 0)>(vb), h2 = tr_read<v_rd_off(D0, 2, 1)>(vb), l3 = tr_read<v_rd_off(D0, 3, 0)>(vb), h3 = tr_read<v_rd_off(D0, 3, 1)>(vb);
;     asm volatile("s_waitcnt lgkmcnt(0)" ::: "memory"); SBAR();
;     ...
;     od = __builtin_amdgcn_mfma_f32_32x32x16_bf16(pa0, PK(l0, h0), od, 0, 0, 0);
;     od = __builtin_amdgcn_mfma_f32_32x32x16_bf16(pa1, PK(l1, h1), od, 0, 0, 0);
;     od = __builtin_amdgcn_mfma_f32_32x32x16_bf16(pa2, PK(l2, h2), od, 0, 0, 0);
;     od = __builtin_amdgcn_mfma_f32_32x32x16_bf16(pa3, PK(l3, h3), od, 0, 0, 0);
;     ...
; }
; __device__ __forceinline__ void pv_d0(f32x16* o, int vb, bf16x8 pa0, bf16x8 pa1, bf16x8 pa2, bf16x8 pa3) {
;     pv_one<0>(o[0], vb, pa0, pa1, pa2, pa3); pv_one<1>(o[1], vb, pa0, pa1, pa2, pa3); pv_one<2>(o[2], vb, pa0, pa1, pa2, pa3); pv_one<3>(o[3], vb, pa0, pa1, pa2, pa3);
; }
; __device__ __forceinline__ void partialSM(f32x16& p0, f32x16& p1, float& m_reg, float& mn, float& alpha, const float C, const float thr) {
;     float pmax = p0[0];
; #pragma unroll
;     for (int r = 1; r < 16; ++r) pmax = fmaxf(pmax, p0[r]);
; #pragma unroll
;     for (int r = 0; r < 16; ++r) pmax = fmaxf(pmax, p1[r]);
;     { auto rr = __builtin_amdgcn_permlane32_swap(__float_as_uint(pmax), __float_as_uint(pmax), false, false);
;       pmax = fmaxf(__uint_as_float(rr[0]), __uint_as_float(rr[1])); }
;     if (__builtin_expect(__all(pmax - m_reg <= thr), 1)) { mn = m_reg; alpha = 1.f; }
;     else { mn = fmaxf(m_reg, pmax); alpha = __builtin_amdgcn_exp2f((m_reg - mn) * C); m_reg = mn; }
;     const float mnC = -mn * C;
; #pragma unroll
;     for (int r = 0; r < 16; ++r) p0[r] = fmaf(p0[r], C, mnC);
; #pragma unroll
;     for (int r = 0; r < 16; ++r) p1[r] = fmaf(p1[r], C, mnC);
; #pragma unroll
;     for (int r = 0; r < 16; ++r) p0[r] = __builtin_amdgcn_exp2f(p0[r]);
	v_mfma_f32_32x32x16_bf16 v[32:47], v[138:141], v[216:219], v[32:47]
	ds_read_b64_tr_b16 v[216:217], v180 offset:0x400
	ds_read_b64_tr_b16 v[218:219], v180 offset:0xc00
	v_permlane32_swap_b32_e32 v238, v239
	v_max_f32_e32 v239, v239, v239
	v_max_f32_e32 v238, v238, v238
	v_max_f32_e32 v238, v238, v239
	v_sub_f32_e32 v239, v238, v142
	s_waitcnt lgkmcnt(6)
	v_mfma_f32_32x32x16_bf16 v[32:47], v[204:207], v[220:223], v[32:47]
	ds_read_b64_tr_b16 v[220:221], v180 offset:0x1400
	ds_read_b64_tr_b16 v[222:223], v180 offset:0x1c00
	v_cmp_ge_f32_e32 vcc, s76, v239
	v_max_f32_e32 v239, v142, v142
	v_max_f32_e32 v238, v239, v238
	v_sub_f32_e32 v239, v142, v238
	v_mul_f32_e32 v239, 0x3e38aa3b, v239
	s_waitcnt lgkmcnt(6)
	v_mfma_f32_32x32x16_bf16 v[32:47], v[144:147], v[224:227], v[32:47]
	ds_read_b64_tr_b16 v[224:225], v180 offset:0x2400
	ds_read_b64_tr_b16 v[226:227], v180 offset:0x2c00
	v_exp_f32_e32 v239, v239
	s_cmp_eq_u64 vcc, exec
	s_cselect_b64 s[14:15], -1, 0
	v_cndmask_b32_e64 v200, v239, 1.0, s[14:15]
	v_cmp_gt_f32_e32 vcc, 1.0, v200
	s_waitcnt lgkmcnt(6)
	v_mfma_f32_32x32x16_bf16 v[32:47], v[148:151], v[228:231], v[32:47]
	ds_read_b64_tr_b16 v[228:229], v180 offset:0x3400
	ds_read_b64_tr_b16 v[230:231], v180 offset:0x3c00
	v_cndmask_b32_e64 v241, v238, v142, s[14:15]
	v_mul_f32_e32 v239, 0xbe38aa3b, v241
	v_fmamk_f32 v80, v80, 0x3e38aa3b, v239
	v_fmamk_f32 v81, v81, 0x3e38aa3b, v239
	v_fmamk_f32 v82, v82, 0x3e38aa3b, v239
	s_waitcnt lgkmcnt(6)
	v_mfma_f32_32x32x16_bf16 v[16:31], v[138:141], v[216:219], v[16:31]
	ds_read_b64_tr_b16 v[216:217], v180 offset:0x600
	ds_read_b64_tr_b16 v[218:219], v180 offset:0xe00
	v_fmamk_f32 v83, v83, 0x3e38aa3b, v239
	v_fmamk_f32 v84, v84, 0x3e38aa3b, v239
	v_fmamk_f32 v85, v85, 0x3e38aa3b, v239
	v_fmamk_f32 v86, v86, 0x3e38aa3b, v239
	v_fmamk_f32 v87, v87, 0x3e38aa3b, v239
	s_waitcnt lgkmcnt(6)
	v_mfma_f32_32x32x16_bf16 v[16:31], v[204:207], v[220:223], v[16:31]
	ds_read_b64_tr_b16 v[220:221], v180 offset:0x1600
	ds_read_b64_tr_b16 v[222:223], v180 offset:0x1e00
	v_fmamk_f32 v88, v88, 0x3e38aa3b, v239
	v_fmamk_f32 v89, v89, 0x3e38aa3b, v239
	v_fmamk_f32 v90, v90, 0x3e38aa3b, v239
	v_fmamk_f32 v91, v91, 0x3e38aa3b, v239
	v_fmamk_f32 v92, v92, 0x3e38aa3b, v239
	s_waitcnt lgkmcnt(6)
	v_mfma_f32_32x32x16_bf16 v[16:31], v[144:147], v[224:227], v[16:31]
	ds_read_b64_tr_b16 v[224:225], v180 offset:0x2600
	ds_read_b64_tr_b16 v[226:227], v180 offset:0x2e00
	v_fmamk_f32 v93, v93, 0x3e38aa3b, v239
	v_fmamk_f32 v94, v94, 0x3e38aa3b, v239
	v_fmamk_f32 v95, v95, 0x3e38aa3b, v239
	s_waitcnt lgkmcnt(6)
	v_mfma_f32_32x32x16_bf16 v[16:31], v[148:151], v[228:231], v[16:31]
	ds_read_b64_tr_b16 v[228:229], v180 offset:0x3600
	ds_read_b64_tr_b16 v[230:231], v180 offset:0x3e00
	v_exp_f32_e32 v153, v81
	v_exp_f32_e32 v152, v83
	s_waitcnt lgkmcnt(6)
	v_mfma_f32_32x32x16_bf16 v[0:15], v[138:141], v[216:219], v[0:15]
	v_exp_f32_e32 v142, v88
	v_exp_f32_e32 v143, v90
	v_exp_f32_e32 v138, v80
	v_exp_f32_e32 v139, v82
	s_waitcnt lgkmcnt(4)
	v_mfma_f32_32x32x16_bf16 v[0:15], v[204:207], v[220:223], v[0:15]
	v_exp_f32_e32 v140, v84
	v_exp_f32_e32 v141, v86
	s_waitcnt lgkmcnt(2)
	v_mfma_f32_32x32x16_bf16 v[0:15], v[144:147], v[224:227], v[0:15]
	v_exp_f32_e32 v144, v92
	v_exp_f32_e32 v147, v93
	s_waitcnt lgkmcnt(0)
	v_mfma_f32_32x32x16_bf16 v[0:15], v[148:151], v[228:231], v[0:15]
	v_exp_f32_e32 v145, v94
	v_exp_f32_e32 v146, v95
	s_barrier
	s_waitcnt vmcnt(5)
	ds_write_b128 v181, v[114:117]
	s_waitcnt vmcnt(4)
	ds_write_b128 v184, v[118:121]
	s_waitcnt vmcnt(3)
	ds_write_b128 v182, v[122:125] offset:32768
	s_cbranch_vccz .LBB0_175
	s_and_saveexec_b64 s[38:39], s[12:13]
	ds_write_b32 v177, v200 offset:49280
	s_or_b64 exec, exec, s[38:39]
	s_waitcnt lgkmcnt(0)
	v_add_u32_e32 v242, v161, v96
	ds_read_b128 v[244:247], v242 offset:49376
	ds_read_b128 v[148:151], v242 offset:49344
	ds_read_b128 v[204:207], v242 offset:49312
	ds_read_b128 v[216:219], v242 offset:49280
	s_waitcnt lgkmcnt(3)
	v_pk_mul_f32 v[60:61], v[60:61], v[244:245]
	s_waitcnt lgkmcnt(2)
	v_pk_mul_f32 v[56:57], v[56:57], v[148:149]
	s_waitcnt lgkmcnt(1)
	v_pk_mul_f32 v[52:53], v[52:53], v[204:205]
	v_pk_mul_f32 v[62:63], v[62:63], v[246:247]
	v_pk_mul_f32 v[58:59], v[58:59], v[150:151]
	v_pk_mul_f32 v[54:55], v[54:55], v[206:207]
	s_waitcnt lgkmcnt(0)
	v_pk_mul_f32 v[50:51], v[50:51], v[218:219]
	v_pk_mul_f32 v[48:49], v[48:49], v[216:217]
	v_pk_mul_f32 v[44:45], v[44:45], v[244:245]
	v_pk_mul_f32 v[40:41], v[40:41], v[148:149]
	v_pk_mul_f32 v[36:37], v[36:37], v[204:205]
	v_pk_mul_f32 v[46:47], v[46:47], v[246:247]
	v_pk_mul_f32 v[42:43], v[42:43], v[150:151]
	v_pk_mul_f32 v[38:39], v[38:39], v[206:207]
	v_pk_mul_f32 v[34:35], v[34:35], v[218:219]
	v_pk_mul_f32 v[32:33], v[32:33], v[216:217]
	v_pk_mul_f32 v[28:29], v[28:29], v[244:245]
	v_pk_mul_f32 v[24:25], v[24:25], v[148:149]
	v_pk_mul_f32 v[20:21], v[20:21], v[204:205]
	v_pk_mul_f32 v[30:31], v[30:31], v[246:247]
	v_pk_mul_f32 v[26:27], v[26:27], v[150:151]
	v_pk_mul_f32 v[22:23], v[22:23], v[206:207]
	v_pk_mul_f32 v[18:19], v[18:19], v[218:219]
	v_pk_mul_f32 v[16:17], v[16:17], v[216:217]
	v_pk_mul_f32 v[12:13], v[12:13], v[244:245]
	v_pk_mul_f32 v[8:9], v[8:9], v[148:149]
	v_pk_mul_f32 v[4:5], v[4:5], v[204:205]
	v_pk_mul_f32 v[14:15], v[14:15], v[246:247]
	v_pk_mul_f32 v[10:11], v[10:11], v[150:151]
	v_pk_mul_f32 v[6:7], v[6:7], v[206:207]
	v_pk_mul_f32 v[2:3], v[2:3], v[218:219]
	v_pk_mul_f32 v[0:1], v[0:1], v[216:217]

; #define SBAR() __builtin_amdgcn_sched_barrier(0)
; template <int OFF> __device__ __forceinline__ s16x4 tr_read(int vb) { s16x4 r; asm volatile("ds_read_b64_tr_b16 %0, %1 offset:%2" : "=&v"(r) : "v"(vb), "i"(OFF) : "memory"); return r; }
; template <int D0> __device__ __forceinline__ void pv_one(f32x16& od, int vb, bf16x8 pa0, bf16x8 pa1, bf16x8 pa2, bf16x8 pa3) {
;     const s16x4 l0 = tr_read<v_rd_off(D0, 0, 0)>(vb), h0 = tr_read<v_rd_off(D0, 0, 1)>(vb), l1 = tr_read<v_rd_off(D0, 1, 0)>(vb), h1 = tr_read<v_rd_off(D0, 1, 1)>(vb);
;     const s16x4 l2 = tr_read<v_rd_off(D0, 2, 0)>(vb), h2 = tr_read<v_rd_off(D0, 2, 1)>(vb), l3 = tr_read<v_rd_off(D0, 3, 0)>(vb), h3 = tr_read<v_rd_off(D0, 3, 1)>(vb);
;     asm volatile("s_waitcnt lgkmcnt(0)" ::: "memory"); SBAR();
;     ...
;     od = __builtin_amdgcn_mfma_f32_32x32x16_bf16(pa0, PK(l0, h0), od, 0, 0, 0);
;     od = __builtin_amdgcn_mfma_f32_32x32x16_bf16(pa1, PK(l1, h1), od, 0, 0, 0);
;     od = __builtin_amdgcn_mfma_f32_32x32x16_bf16(pa2, PK(l2, h2), od, 0, 0, 0);
;     od = __builtin_amdgcn_mfma_f32_32x32x16_bf16(pa3, PK(l3, h3), od, 0, 0, 0);
;     ...
; }
; __device__ __forceinline__ void pv_d0(f32x16* o, int vb, bf16x8 pa0, bf16x8 pa1, bf16x8 pa2, bf16x8 pa3) {
;     pv_one<0>(o[0], vb, pa0, pa1, pa2, pa3); pv_one<1>(o[1], vb, pa0, pa1, pa2, pa3); pv_one<2>(o[2], vb, pa0, pa1, pa2, pa3); pv_one<3>(o[3], vb, pa0, pa1, pa2, pa3);
; }
; __device__ __forceinline__ void partialSM(f32x16& p0, f32x16& p1, float& m_reg, float& mn, float& alpha, const float C, const float thr) {
;     float pmax = p0[0];
; #pragma unroll
;     for (int r = 1; r < 16; ++r) pmax = fmaxf(pmax, p0[r]);
; #pragma unroll
;     for (int r = 0; r < 16; ++r) pmax = fmaxf(pmax, p1[r]);
;     { auto rr = __builtin_amdgcn_permlane32_swap(__float_as_uint(pmax), __float_as_uint(pmax), false, false);
;       pmax = fmaxf(__uint_as_float(rr[0]), __uint_as_float(rr[1])); }
;     if (__builtin_expect(__all(pmax - m_reg <= thr), 1)) { mn = m_reg; alpha = 1.f; }
;     else { mn = fmaxf(m_reg, pmax); alpha = __builtin_amdgcn_exp2f((m_reg - mn) * C); m_reg = mn; }
;     const float mnC = -mn * C;
; #pragma unroll
;     for (int r = 0; r < 16; ++r) p0[r] = fmaf(p0[r], C, mnC);
; #pragma unroll
;     for (int r = 0; r < 16; ++r) p1[r] = fmaf(p1[r], C, mnC);
; #pragma unroll
;     for (int r = 0; r < 16; ++r) p0[r] = __builtin_amdgcn_exp2f(p0[r]);
.LBB0_177:
	s_waitcnt lgkmcnt(0)
	s_nop 0
	v_mfma_f32_32x32x16_bf16 v[48:63], v[138:141], v[216:219], v[48:63]
	ds_read_b64_tr_b16 v[216:217], v179 offset:0x200
	ds_read_b64_tr_b16 v[218:219], v179 offset:0xa00
	v_max_f32_e32 v238, v81, v81
	v_max_f32_e32 v239, v80, v80
	v_max_f32_e32 v238, v239, v238
	v_max3_f32 v238, v238, v82, v83
	v_max3_f32 v238, v238, v84, v85
	v_mfma_f32_32x32x16_bf16 v[48:63], v[142:145], v[220:223], v[48:63]
	ds_read_b64_tr_b16 v[220:221], v179 offset:0x1200
	ds_read_b64_tr_b16 v[222:223], v179 offset:0x1a00
	v_max3_f32 v238, v238, v86, v87
	v_max3_f32 v238, v238, v88, v89
	v_max3_f32 v238, v238, v90, v91
	v_max3_f32 v238, v238, v92, v93
	v_max3_f32 v238, v238, v94, v95
	v_mfma_f32_32x32x16_bf16 v[48:63], v[146:149], v[224:227], v[48:63]
	ds_read_b64_tr_b16 v[224:225], v179 offset:0x2200
	ds_read_b64_tr_b16 v[226:227], v179 offset:0x2a00
	v_max3_f32 v238, v238, v64, v65
	v_max3_f32 v238, v238, v66, v67
	v_max3_f32 v238, v238, v68, v69
	v_max3_f32 v238, v238, v70, v71
	v_max3_f32 v238, v238, v72, v73
	v_mfma_f32_32x32x16_bf16 v[48:63], v[150:153], v[228:231], v[48:63]
	ds_read_b64_tr_b16 v[228:229], v179 offset:0x3200
	ds_read_b64_tr_b16 v[230:231], v179 offset:0x3a00
	v_max3_f32 v238, v238, v74, v75
	v_max3_f32 v238, v238, v76, v77
	v_max3_f32 v238, v238, v78, v79
	v_mov_b32_e32 v239, v238
	s_nop 1
	s_waitcnt lgkmcnt(6)
	v_mfma_f32_32x32x16_bf16 v[32:47], v[138:141], v[216:219], v[32:47]
	ds_read_b64_tr_b16 v[216:217], v179 offset:0x400
	ds_read_b64_tr_b16 v[218:219], v179 offset:0xc00
	v_permlane32_swap_b32_e32 v238, v239
	v_max_f32_e32 v239, v239, v239
	v_max_f32_e32 v238, v238, v238
	v_max_f32_e32 v238, v238, v239
	v_sub_f32_e32 v239, v238, v202
	s_waitcnt lgkmcnt(6)
	v_mfma_f32_32x32x16_bf16 v[32:47], v[142:145], v[220:223], v[32:47]
	ds_read_b64_tr_b16 v[220:221], v179 offset:0x1400
	ds_read_b64_tr_b16 v[222:223], v179 offset:0x1c00
	v_cmp_ge_f32_e32 vcc, s76, v239
	v_max_f32_e32 v239, v202, v202
	v_max_f32_e32 v238, v239, v238
	v_sub_f32_e32 v239, v202, v238
	v_mul_f32_e32 v239, 0x3e38aa3b, v239
	s_waitcnt lgkmcnt(6)
	v_mfma_f32_32x32x16_bf16 v[32:47], v[146:149], v[224:227], v[32:47]
	ds_read_b64_tr_b16 v[224:225], v179 offset:0x2400
	ds_read_b64_tr_b16 v[226:227], v179 offset:0x2c00
	v_exp_f32_e32 v239, v239
	s_cmp_eq_u64 vcc, exec
	s_cselect_b64 s[14:15], -1, 0
	v_cndmask_b32_e64 v240, v239, 1.0, s[14:15]
	v_cmp_gt_f32_e32 vcc, 1.0, v240
	s_waitcnt lgkmcnt(6)
	v_mfma_f32_32x32x16_bf16 v[32:47], v[150:153], v[228:231], v[32:47]
	ds_read_b64_tr_b16 v[228:229], v179 offset:0x3400
	ds_read_b64_tr_b16 v[230:231], v179 offset:0x3c00
	v_cndmask_b32_e64 v241, v238, v202, s[14:15]
	v_mul_f32_e32 v239, 0xbe38aa3b, v241
	v_fmamk_f32 v80, v80, 0x3e38aa3b, v239
	v_fmamk_f32 v81, v81, 0x3e38aa3b, v239
	v_fmamk_f32 v82, v82, 0x3e38aa3b, v239
	s_waitcnt lgkmcnt(6)
	v_mfma_f32_32x32x16_bf16 v[16:31], v[138:141], v[216:219], v[16:31]
	ds_read_b64_tr_b16 v[216:217], v179 offset:0x600
	ds_read_b64_tr_b16 v[218:219], v179 offset:0xe00
	v_fmamk_f32 v83, v83, 0x3e38aa3b, v239
	v_fmamk_f32 v84, v84, 0x3e38aa3b, v239
	v_fmamk_f32 v85, v85, 0x3e38aa3b, v239
	v_fmamk_f32 v86, v86, 0x3e38aa3b, v239
	v_fmamk_f32 v87, v87, 0x3e38aa3b, v239
	s_waitcnt lgkmcnt(6)
	v_mfma_f32_32x32x16_bf16 v[16:31], v[142:145], v[220:223], v[16:31]
	ds_read_b64_tr_b16 v[220:221], v179 offset:0x1600
	ds_read_b64_tr_b16 v[222:223], v179 offset:0x1e00
	v_fmamk_f32 v88, v88, 0x3e38aa3b, v239
	v_fmamk_f32 v89, v89, 0x3e38aa3b, v239
	v_fmamk_f32 v90, v90, 0x3e38aa3b, v239
	v_fmamk_f32 v91, v91, 0x3e38aa3b, v239
	v_fmamk_f32 v92, v92, 0x3e38aa3b, v239
	s_waitcnt lgkmcnt(6)
	v_mfma_f32_32x32x16_bf16 v[16:31], v[146:149], v[224:227], v[16:31]
	ds_read_b64_tr_b16 v[224:225], v179 offset:0x2600
	ds_read_b64_tr_b16 v[226:227], v179 offset:0x2e00
	v_fmamk_f32 v93, v93, 0x3e38aa3b, v239
	v_fmamk_f32 v94, v94, 0x3e38aa3b, v239
	s_waitcnt lgkmcnt(6)
	v_mfma_f32_32x32x16_bf16 v[16:31], v[150:153], v[228:231], v[16:31]
	ds_read_b64_tr_b16 v[228:229], v179 offset:0x3600
	ds_read_b64_tr_b16 v[230:231], v179 offset:0x3e00
	v_exp_f32_e32 v208, v82
	v_exp_f32_e32 v202, v87
	s_waitcnt lgkmcnt(6)
	v_mfma_f32_32x32x16_bf16 v[0:15], v[138:141], v[216:219], v[0:15]
	v_exp_f32_e32 v217, v80
	v_exp_f32_e32 v219, v81
	s_waitcnt lgkmcnt(4)
	v_mfma_f32_32x32x16_bf16 v[0:15], v[142:145], v[220:223], v[0:15]
	v_exp_f32_e32 v145, v92
	v_exp_f32_e32 v144, v94
	v_exp_f32_e32 v218, v83
	v_exp_f32_e32 v216, v85
	s_waitcnt lgkmcnt(2)
	v_mfma_f32_32x32x16_bf16 v[0:15], v[146:149], v[224:227], v[0:15]
	v_exp_f32_e32 v147, v90
	v_exp_f32_e32 v148, v93
	s_waitcnt lgkmcnt(0)
	v_mfma_f32_32x32x16_bf16 v[0:15], v[150:153], v[228:231], v[0:15]
	v_exp_f32_e32 v149, v88
	v_mov_b32_e32 v143, v240
	s_barrier
	s_waitcnt vmcnt(2)
	ds_write_b128 v181, v[126:129] offset:16384
	s_waitcnt vmcnt(1)
	ds_write_b128 v184, v[130:133] offset:16384
	s_waitcnt vmcnt(0)
	ds_write_b128 v182, v[134:137] offset:40960
	s_cbranch_vccz .LBB0_181
	s_and_saveexec_b64 s[38:39], s[12:13]
	ds_write_b32 v177, v143 offset:49280
	s_or_b64 exec, exec, s[38:39]
	s_waitcnt lgkmcnt(0)
	v_add_u32_e32 v139, v161, v96
	ds_read_b128 v[126:129], v139 offset:49376
	ds_read_b128 v[130:133], v139 offset:49344
	ds_read_b128 v[134:137], v139 offset:49312
	ds_read_b128 v[244:247], v139 offset:49280
	s_waitcnt lgkmcnt(3)
	v_pk_mul_f32 v[60:61], v[60:61], v[126:127]
	s_waitcnt lgkmcnt(2)
	v_pk_mul_f32 v[56:57], v[56:57], v[130:131]
	s_waitcnt lgkmcnt(1)
	v_pk_mul_f32 v[52:53], v[52:53], v[134:135]
	v_pk_mul_f32 v[62:63], v[62:63], v[128:129]
	v_pk_mul_f32 v[58:59], v[58:59], v[132:133]
	v_pk_mul_f32 v[54:55], v[54:55], v[136:137]
	s_waitcnt lgkmcnt(0)
	v_pk_mul_f32 v[50:51], v[50:51], v[246:247]
	v_pk_mul_f32 v[48:49], v[48:49], v[244:245]
	v_pk_mul_f32 v[44:45], v[44:45], v[126:127]
	v_pk_mul_f32 v[40:41], v[40:41], v[130:131]
	v_pk_mul_f32 v[36:37], v[36:37], v[134:135]
	v_pk_mul_f32 v[46:47], v[46:47], v[128:129]
	v_pk_mul_f32 v[42:43], v[42:43], v[132:133]
	v_pk_mul_f32 v[38:39], v[38:39], v[136:137]
	v_pk_mul_f32 v[34:35], v[34:35], v[246:247]
	v_pk_mul_f32 v[32:33], v[32:33], v[244:245]
	v_pk_mul_f32 v[28:29], v[28:29], v[126:127]
	v_pk_mul_f32 v[24:25], v[24:25], v[130:131]
	v_pk_mul_f32 v[20:21], v[20:21], v[134:135]
	v_pk_mul_f32 v[30:31], v[30:31], v[128:129]
	v_pk_mul_f32 v[26:27], v[26:27], v[132:133]
	v_pk_mul_f32 v[22:23], v[22:23], v[136:137]
	v_pk_mul_f32 v[18:19], v[18:19], v[246:247]
	v_pk_mul_f32 v[16:17], v[16:17], v[244:245]
	v_pk_mul_f32 v[12:13], v[12:13], v[126:127]
	v_pk_mul_f32 v[8:9], v[8:9], v[130:131]
	v_pk_mul_f32 v[4:5], v[4:5], v[134:135]
	v_pk_mul_f32 v[14:15], v[14:15], v[128:129]
	v_pk_mul_f32 v[10:11], v[10:11], v[132:133]
	v_pk_mul_f32 v[6:7], v[6:7], v[136:137]
	v_pk_mul_f32 v[2:3], v[2:3], v[246:247]
	v_pk_mul_f32 v[0:1], v[0:1], v[244:245]
